# attnA in-loop group barriers: two counter reads kept in flight while polling
# speedup vs baseline: 1.0026x; 1.0026x over previous
.LBB0_1377:
	v_mov_b32_e32 v0, s33
	ds_read_b32 v248, v0 offset:8
.Lp2_0:
	ds_read_b32 v249, v0 offset:8
	s_waitcnt lgkmcnt(1)
	v_cmp_gt_u32_e32 vcc, s17, v248
	s_cbranch_vccz .Lp2d_0
	ds_read_b32 v248, v0 offset:8
	s_waitcnt lgkmcnt(1)
	v_cmp_gt_u32_e32 vcc, s17, v249
	s_cbranch_vccnz .Lp2_0
.Lp2d_0:
	s_waitcnt lgkmcnt(0)

.Lp2_1:
	ds_read_b32 v249, v0 offset:8
	s_waitcnt lgkmcnt(1)
	v_cmp_gt_u32_e32 vcc, s4, v248
	s_cbranch_vccz .Lp2d_1
	ds_read_b32 v248, v0 offset:8
	s_waitcnt lgkmcnt(1)
	v_cmp_gt_u32_e32 vcc, s4, v249
	s_cbranch_vccnz .Lp2_1

.Lp2_3:
	ds_read_b32 v249, v0 offset:8
	s_waitcnt lgkmcnt(1)
	v_cmp_gt_u32_e32 vcc, s81, v248
	s_cbranch_vccz .Lp2d_3
	ds_read_b32 v248, v0 offset:8
	s_waitcnt lgkmcnt(1)
	v_cmp_gt_u32_e32 vcc, s81, v249
	s_cbranch_vccnz .Lp2_3
